# tail spreading: leftover tiles of the last GEMM/merge round go to the first workgroup of distinct CUs (CU-pair handshake at start)
# speedup vs baseline: 1.0193x; 1.0193x over previous
.LBB0_5:
	s_or_b64 exec, exec, s[2:3]
	s_load_dwordx2 s[98:99], s[0:1], 0x178
	s_getreg_b32 s101, hwreg(HW_REG_HW_ID, 8, 7)
	s_and_b32 s100, s20, 7
	s_lshl_b32 s100, s100, 7
	s_or_b32 s101, s101, s100
	s_lshl_b32 s101, s101, 2
	v_cmp_eq_u32_e32 vcc, 0, v194
	s_and_saveexec_b64 s[2:3], vcc
	s_cbranch_execz .Lab_skip
	v_mov_b32_e32 v5, s101
	v_mov_b32_e32 v2, 1
	s_waitcnt lgkmcnt(0)
	global_atomic_add v1, v5, v2, s[98:99] offset:512 sc0
	s_waitcnt vmcnt(0)
	v_readfirstlane_b32 s100, v1
	s_and_b32 vcc_lo, s100, 0xff
	s_cmp_lg_u32 vcc_lo, 0
	s_cbranch_scc1 .Lpair_wait
	s_and_b32 s100, s20, 7
	s_lshl_b32 s100, s100, 2
	s_add_u32 s100, s100, 0x4600
	v_mov_b32_e32 v3, s100
	global_atomic_add v3, v3, v2, s[98:99] sc0
	s_waitcnt vmcnt(0)
	v_add_u32_e32 v4, 1, v3
	v_lshlrev_b32_e32 v4, 8, v4
	global_atomic_add v5, v4, s[98:99] offset:512
	s_branch .Lpair_have
.Lpair_wait:
	v_mov_b32_e32 v2, 0
.Lpair_spin:
	s_lshr_b32 s100, s100, 8
	s_cmp_lg_u32 s100, 0
	s_cbranch_scc1 .Lpair_got
	s_sleep 2
	global_atomic_add v3, v5, v2, s[98:99] offset:512 sc0
	s_waitcnt vmcnt(0)
	v_readfirstlane_b32 s100, v3
	s_branch .Lpair_spin
.Lpair_got:
	s_add_i32 s100, s100, -1
	v_mov_b32_e32 v3, s100
.Lpair_have:
	s_nop 0
	v_readfirstlane_b32 s100, v3
	s_and_b32 vcc_hi, s20, 7
	s_lshl_b32 vcc_hi, vcc_hi, 5
	s_and_b32 s100, s100, 31
	s_or_b32 s100, s100, vcc_hi
	s_lshl_b32 s100, s100, 8
	s_cmp_eq_u32 vcc_lo, 0
	s_cselect_b32 vcc_hi, 0x10000, 0
	s_or_b32 s100, s100, vcc_hi
	s_and_b32 vcc_lo, vcc_lo, 1
	s_or_b32 s100, s100, vcc_lo
	v_mov_b32_e32 v1, s100
	v_mov_b32_e32 v2, 0x10018
	ds_write_b32 v2, v1
	s_waitcnt vmcnt(0) lgkmcnt(0)
.Lab_skip:
	s_or_b64 exec, exec, s[2:3]
	s_waitcnt lgkmcnt(0)
	s_barrier
	v_mov_b32_e32 v1, 0x10018
	ds_read_b32 v1, v1
	v_lshrrev_b32_e32 v2, 6, v194
	s_waitcnt lgkmcnt(0)
	s_nop 0
	v_readfirstlane_b32 s101, v1
	v_readfirstlane_b32 s100, v2
	s_and_b32 s101, s101, 1
	s_getreg_b32 s98, hwreg(HW_REG_HW_ID, 4, 2)
	s_getreg_b32 s99, hwreg(HW_REG_HW_ID, 0, 1)
	s_lshl_b32 s99, s99, 4
	s_or_b32 s99, s99, s98
	v_mov_b32_e32 v1, s99
	v_lshlrev_b32_e32 v2, 2, v2
	v_add_u32_e32 v2, 0x10000, v2
	ds_write_b32 v2, v1
	s_waitcnt lgkmcnt(0)
	s_barrier
	v_mov_b32_e32 v2, 0x10000
	ds_read_b32 v1, v2
	ds_read_b32 v3, v2 offset:4
	ds_read_b32 v4, v2 offset:8
	ds_read_b32 v5, v2 offset:12
	s_waitcnt lgkmcnt(0)
	v_and_b32_e32 v6, v1, v3
	v_and_b32_e32 v7, v4, v5
	v_and_b32_e32 v6, v6, v7
	v_or3_b32 v7, v1, v3, v4
	v_or_b32_e32 v7, v7, v5
	v_xor_b32_e32 v6, v6, v7
	v_and_b32_e32 v1, 3, v1
	v_and_b32_e32 v3, 3, v3
	v_and_b32_e32 v4, 3, v4
	v_and_b32_e32 v5, 3, v5
	v_lshlrev_b32_e64 v1, v1, 1
	v_lshlrev_b32_e64 v3, v3, 1
	v_lshlrev_b32_e64 v4, v4, 1
	v_lshlrev_b32_e64 v5, v5, 1
	v_or3_b32 v1, v1, v3, v4
	v_or_b32_e32 v1, v1, v5
	s_nop 0
	v_readfirstlane_b32 s99, v1
	v_readfirstlane_b32 vcc_lo, v6
	s_bitcmp1_b32 vcc_lo, 4
	s_cbranch_scc1 .Lab_keep
	s_getreg_b32 s101, hwreg(HW_REG_HW_ID, 0, 1)

.Lrole_done:
	s_lshl_b32 s98, s98, 1
	s_or_b32 s99, s99, s98
	s_lshl_b32 s100, s100, 2
	s_or_b32 s101, s99, s100
	v_readlane_b32 s98, v252, 0
	s_lshr_b32 s98, s98, 3
	s_and_b32 s98, s98, 0xff
	s_lshl_b32 s98, s98, 8
	s_or_b32 s101, s101, s98
	v_mov_b32_e32 v1, 0x10018
	ds_read_b32 v1, v1
	s_waitcnt lgkmcnt(0)
	s_nop 0
	v_readfirstlane_b32 s98, v1
	s_lshr_b32 s98, s98, 8
	s_lshl_b32 s98, s98, 16
	s_or_b32 s101, s101, s98
	v_readlane_b32 s98, v252, 0
	s_lshr_b32 s99, s98, 3
	s_and_b32 s98, s98, 7
	s_and_b32 s100, s99, 15
	s_lshl_b32 s100, s100, 2
	s_lshr_b32 s99, s99, 4
	s_or_b32 s99, s99, s100
	s_lshl_b32 s99, s99, 3
	s_or_b32 s98, s98, s99
	s_nop 0
	v_writelane_b32 v252, s98, 0
	s_load_dwordx2 s[52:53], s[0:1], 0x210
	s_waitcnt lgkmcnt(0)
	s_cmp_ge_i32 s52, s53
	s_cbranch_scc1 .Lend_near
	s_load_dwordx2 s[22:23], s[0:1], 0x1a8
	s_load_dwordx16 s[56:71], s[0:1], 0x0
	s_load_dwordx16 s[36:51], s[0:1], 0x40
	s_load_dwordx16 s[4:19], s[0:1], 0x80
	v_lshrrev_b32_e32 v1, 20, v0
	v_lshrrev_b32_e32 v0, 10, v0
	v_or_b32_e32 v0, v0, v1
	s_mov_b32 s97, 0
	s_waitcnt lgkmcnt(0)
	v_writelane_b32 v252, s4, 5
	s_movk_i32 s55, 0x4000
	v_mov_b32_e32 v2, 0
	v_writelane_b32 v252, s5, 6
	v_writelane_b32 v252, s6, 7
	v_writelane_b32 v252, s7, 8
	v_writelane_b32 v252, s8, 9
	v_writelane_b32 v252, s9, 10
	v_writelane_b32 v252, s10, 11
	v_writelane_b32 v252, s11, 12
	v_writelane_b32 v252, s12, 13
	v_writelane_b32 v252, s13, 14
	v_writelane_b32 v252, s14, 15
	v_writelane_b32 v252, s15, 16
	v_writelane_b32 v252, s16, 17
	v_writelane_b32 v252, s17, 18
	v_writelane_b32 v252, s18, 19
	v_writelane_b32 v252, s19, 20
	s_load_dwordx16 s[4:19], s[0:1], 0xc0
	s_mov_b32 s28, 0x10000
	v_mov_b32_e32 v198, 0x358637bd
	s_movk_i32 s96, 0x43ff
	s_mov_b32 s29, 0x20000
	s_waitcnt lgkmcnt(0)
	v_writelane_b32 v252, s4, 21
	v_mov_b32_e32 v199, 0x10000
	s_movk_i32 s33, 0x110
	v_writelane_b32 v252, s5, 22
	v_writelane_b32 v252, s6, 23
	v_writelane_b32 v252, s7, 24
	v_writelane_b32 v252, s8, 25
	v_writelane_b32 v252, s9, 26
	v_writelane_b32 v252, s10, 27
	v_writelane_b32 v252, s11, 28
	v_writelane_b32 v252, s12, 29
	v_writelane_b32 v252, s13, 30
	v_writelane_b32 v252, s14, 31
	v_writelane_b32 v252, s15, 32
	v_writelane_b32 v252, s16, 33
	v_writelane_b32 v252, s17, 34
	v_writelane_b32 v252, s18, 35
	v_writelane_b32 v252, s19, 36
	s_load_dwordx16 s[4:19], s[0:1], 0x100
	v_mov_b32_e32 v201, 0x3ecc95a3
	v_mov_b64_e32 v[212:213], 0xe00
	v_mov_b64_e32 v[196:197], 0x3600
	v_mov_b32_e32 v204, 0x7f800000
	s_waitcnt lgkmcnt(0)
	v_writelane_b32 v252, s4, 37
	v_mov_b32_e32 v206, 0x41b17218
	v_mov_b32_e32 v136, 0x3f317218
	v_writelane_b32 v252, s5, 38
	v_writelane_b32 v252, s6, 39
	v_writelane_b32 v252, s7, 40
	v_writelane_b32 v252, s8, 41
	v_writelane_b32 v252, s9, 42
	v_writelane_b32 v252, s10, 43
	v_writelane_b32 v252, s11, 44
	v_writelane_b32 v252, s12, 45
	v_writelane_b32 v252, s13, 46
	v_writelane_b32 v252, s14, 47
	v_writelane_b32 v252, s15, 48
	v_writelane_b32 v252, s16, 49
	v_writelane_b32 v252, s17, 50
	v_writelane_b32 v252, s18, 51
	v_writelane_b32 v252, s19, 52
	s_load_dwordx16 s[72:87], s[0:1], 0x140
	s_load_dwordx16 s[4:19], s[0:1], 0x1b0
	v_mov_b32_e32 v203, 0x7fc00000
	v_mov_b32_e32 v195, 0xff800000
	v_mov_b32_e32 v205, 0xe400
	v_mov_b32_e32 v200, 0x9f00
	s_waitcnt lgkmcnt(0)
	v_writelane_b32 v252, s4, 53
	v_mov_b32_e32 v207, 0x42800000
	s_nop 0
	v_writelane_b32 v252, s5, 54
	v_writelane_b32 v252, s6, 55
	v_writelane_b32 v252, s7, 56
	v_writelane_b32 v253, s15, 0
	v_writelane_b32 v252, s8, 57
	v_writelane_b32 v253, s16, 1
	v_writelane_b32 v252, s9, 58
	v_writelane_b32 v253, s17, 2
	v_writelane_b32 v252, s10, 59
	v_writelane_b32 v253, s18, 3
	v_writelane_b32 v252, s11, 60
	v_writelane_b32 v253, s19, 4
	s_load_dwordx8 s[4:11], s[0:1], 0x1f0
	s_add_u32 s0, s0, 0x218
	s_addc_u32 s1, s1, 0
	v_writelane_b32 v252, s12, 61
	v_writelane_b32 v252, s13, 62
	s_waitcnt lgkmcnt(0)
	v_writelane_b32 v253, s4, 5
	v_writelane_b32 v252, s14, 63
	s_nop 0
	v_writelane_b32 v253, s5, 6
	v_writelane_b32 v253, s6, 7
	v_writelane_b32 v253, s7, 8
	v_writelane_b32 v253, s8, 9
	v_writelane_b32 v253, s9, 10
	v_writelane_b32 v253, s10, 11
	v_writelane_b32 v253, s11, 12
	v_writelane_b32 v253, s0, 13
	s_nop 1
	v_writelane_b32 v253, s1, 14
	s_add_u32 s0, s88, 0x200
	s_addc_u32 s1, s89, 0
	v_writelane_b32 v253, s0, 15
	s_nop 1
	v_writelane_b32 v253, s1, 16
	s_add_u32 s0, s88, 0x1000
	s_addc_u32 s1, s89, 0
	v_writelane_b32 v253, s0, 17
	s_nop 1
	v_writelane_b32 v253, s1, 18
	s_add_u32 s0, s88, 0x1100
	s_addc_u32 s1, s89, 0
	v_writelane_b32 v253, s0, 19
	s_nop 1
	v_writelane_b32 v253, s1, 20
	s_add_u32 s0, s88, 0x1200
	s_addc_u32 s1, s89, 0
	v_writelane_b32 v253, s0, 21
	s_nop 1
	v_writelane_b32 v253, s1, 22
	s_add_u32 s0, s88, 0x1300
	s_addc_u32 s1, s89, 0
	v_writelane_b32 v253, s0, 23
	s_cmp_eq_u32 s20, 15
	s_nop 0
	v_writelane_b32 v253, s1, 24
	s_cselect_b64 s[0:1], -1, 0
	v_writelane_b32 v253, s0, 25
	s_cmp_eq_u32 s20, 14
	s_nop 0
	v_writelane_b32 v253, s1, 26
	s_cselect_b64 s[0:1], -1, 0
	v_writelane_b32 v253, s0, 27
	s_cmp_eq_u32 s20, 13
	s_nop 0
	v_writelane_b32 v253, s1, 28
	s_cselect_b64 s[0:1], -1, 0
	v_writelane_b32 v253, s0, 29
	s_cmp_eq_u32 s20, 12
	s_nop 0
	v_writelane_b32 v253, s1, 30
	s_cselect_b64 s[0:1], -1, 0
	v_writelane_b32 v253, s0, 31
	s_cmp_eq_u32 s20, 11
	s_nop 0
	v_writelane_b32 v253, s1, 32
	s_cselect_b64 s[0:1], -1, 0
	v_writelane_b32 v253, s0, 33
	s_cmp_eq_u32 s20, 10
	s_nop 0
	v_writelane_b32 v253, s1, 34
	s_cselect_b64 s[0:1], -1, 0
	v_writelane_b32 v253, s0, 35
	s_cmp_eq_u32 s20, 9
	s_nop 0
	v_writelane_b32 v253, s1, 36
	s_cselect_b64 s[0:1], -1, 0
	v_writelane_b32 v253, s0, 37
	s_cmp_eq_u32 s20, 8
	s_nop 0
	v_writelane_b32 v253, s1, 38
	s_cselect_b64 s[0:1], -1, 0
	v_writelane_b32 v253, s0, 39
	s_cmp_eq_u32 s20, 7
	s_nop 0
	v_writelane_b32 v253, s1, 40
	s_cselect_b64 s[0:1], -1, 0
	v_writelane_b32 v253, s0, 41
	s_cmp_eq_u32 s20, 6
	s_nop 0
	v_writelane_b32 v253, s1, 42
	s_cselect_b64 s[0:1], -1, 0
	v_writelane_b32 v253, s0, 43
	s_cmp_eq_u32 s20, 5
	s_nop 0
	v_writelane_b32 v253, s1, 44
	s_cselect_b64 s[0:1], -1, 0
	v_writelane_b32 v253, s0, 45
	s_cmp_eq_u32 s20, 4
	s_nop 0
	v_writelane_b32 v253, s1, 46
	s_cselect_b64 s[0:1], -1, 0
	v_writelane_b32 v253, s0, 47
	s_cmp_eq_u32 s20, 3
	s_nop 0
	v_writelane_b32 v253, s1, 48
	s_cselect_b64 s[0:1], -1, 0
	v_writelane_b32 v253, s0, 49
	s_cmp_eq_u32 s20, 2
	s_nop 0
	v_writelane_b32 v253, s1, 50
	s_cselect_b64 s[0:1], -1, 0
	v_writelane_b32 v253, s0, 51
	s_cmp_eq_u32 s20, 1
	s_nop 0
	v_writelane_b32 v253, s1, 52
	s_cselect_b64 s[0:1], -1, 0
	v_writelane_b32 v253, s0, 53
	s_cmp_eq_u32 s20, 0
	s_nop 0
	v_writelane_b32 v253, s1, 54
	s_cselect_b64 s[0:1], -1, 0
	v_writelane_b32 v253, s0, 55
	s_nop 1
	v_writelane_b32 v253, s1, 56
	s_lshl_b32 s0, s20, 8
	s_add_u32 s0, s88, s0
	s_addc_u32 s1, s89, 0
	s_add_u32 s2, s0, 0x1400
	s_addc_u32 s3, s1, 0
	v_writelane_b32 v253, s2, 57
	s_add_u32 s0, s0, 0x2400
	s_addc_u32 s1, s1, 0
	v_writelane_b32 v253, s3, 58
	v_writelane_b32 v253, s0, 59
	v_readlane_b32 s3, v252, 0
	s_nop 0
	v_writelane_b32 v253, s1, 60
	s_add_u32 s0, s88, 0x3400
	s_addc_u32 s1, s89, 0
	v_writelane_b32 v253, s0, 61
	s_nop 1
	v_writelane_b32 v253, s1, 62
	s_add_u32 s0, s88, 0x3500
	s_addc_u32 s1, s89, 0
	v_writelane_b32 v253, s0, 63
	s_cmp_lt_i32 s53, 0
	s_nop 0
	v_writelane_b32 v254, s1, 0
	s_cselect_b64 s[0:1], -1, 0
	v_writelane_b32 v254, s0, 1
	s_nop 1
	v_writelane_b32 v254, s1, 2
	s_movk_i32 s0, 0x3ff
	v_and_or_b32 v0, v0, s0, v194
	v_cmp_eq_u32_e64 s[0:1], 0, v0
	s_nop 1
	v_writelane_b32 v254, s0, 3
	s_nop 1
	v_writelane_b32 v254, s1, 4
	s_lshl_b32 s0, s3, 2
	v_writelane_b32 v254, s0, 5
	s_add_u32 s0, s42, 0x1000
	v_writelane_b32 v254, s36, 6
	s_addc_u32 s1, s43, 0
	s_cmp_lg_u64 s[84:85], 0
	v_writelane_b32 v254, s37, 7
	v_writelane_b32 v254, s38, 8
	v_writelane_b32 v254, s39, 9
	v_writelane_b32 v254, s40, 10
	v_writelane_b32 v254, s41, 11
	v_writelane_b32 v254, s42, 12
	v_writelane_b32 v254, s43, 13
	v_writelane_b32 v254, s44, 14
	v_writelane_b32 v254, s45, 15
	v_writelane_b32 v254, s46, 16
	v_writelane_b32 v254, s47, 17
	v_writelane_b32 v254, s48, 18
	v_writelane_b32 v254, s49, 19
	v_writelane_b32 v254, s50, 20
	v_writelane_b32 v254, s51, 21
	v_writelane_b32 v254, s0, 22
	s_mov_b64 s[36:37], 0x800
	s_nop 0
	v_writelane_b32 v254, s1, 23
	s_cselect_b64 s[0:1], -1, 0
	v_writelane_b32 v254, s0, 24
	s_cmpk_lt_i32 s3, 0x1560
	s_nop 0
	v_writelane_b32 v254, s1, 25
	s_cselect_b64 s[0:1], -1, 0
	v_writelane_b32 v254, s0, 26
	s_cmp_lg_u64 s[76:77], 0
	s_nop 0
	v_writelane_b32 v254, s1, 27
	s_cselect_b64 s[0:1], -1, 0
	v_writelane_b32 v254, s0, 28
	s_and_b32 s4, s3, 7
	s_lshl_b32 s2, s3, 4
	v_writelane_b32 v254, s1, 29
	s_lshr_b32 s0, s3, 3
	s_lshl_b32 s1, s4, 6
	v_writelane_b32 v254, s0, 30
	s_add_i32 s0, s1, s0
	v_writelane_b32 v254, s1, 31
	s_lshl_b32 s0, s0, 4
	s_and_b32 s2, s2, 0x380
	s_and_b32 s1, s0, 0xfffffc00
	v_writelane_b32 v254, s2, 32
	s_and_b32 s0, s0, 0x380
	v_writelane_b32 v254, s0, 33
	s_lshl_b32 s0, s3, 1
	s_and_b32 s0, s0, 0x7fffff80
	s_or_b32 s1, s1, s2
	s_addk_i32 s0, 0x4000
	v_writelane_b32 v254, s0, 34
	s_add_i32 s54, s1, 0x2000
	s_lshl_b32 s0, s4, 22
	v_writelane_b32 v254, s1, 35
	s_add_u32 s0, s80, s0
	v_writelane_b32 v254, s4, 36
	s_addc_u32 s1, s81, 0
	v_writelane_b32 v254, s0, 37
	s_nop 1
	v_writelane_b32 v254, s1, 38
	s_add_i32 s1, s22, -1
	s_mul_i32 s0, s1, 0x60
	v_writelane_b32 v254, s0, 39
	s_mul_i32 s0, s1, 0xa0
	v_writelane_b32 v254, s0, 40
	s_ashr_i32 s0, s1, 31
	v_writelane_b32 v254, s0, 41
	v_writelane_b32 v254, s22, 42
	s_sub_i32 s0, 1, s22
	s_max_i32 s0, s1, s0
	v_cvt_f32_u32_e32 v0, s0
	v_writelane_b32 v254, s23, 43
	v_writelane_b32 v254, s1, 44
	v_writelane_b32 v254, s0, 45
	v_rcp_iflag_f32_e32 v0, v0
	s_sub_i32 s0, 0, s0
	v_mul_f32_e32 v0, 0x4f7ffffe, v0
	v_cvt_u32_f32_e32 v0, v0
	s_nop 0
	v_readfirstlane_b32 s1, v0
	s_mul_i32 s0, s0, s1
	s_mul_hi_u32 s0, s1, s0
	s_add_i32 s0, s1, s0
	v_writelane_b32 v254, s0, 46
	s_add_u32 s0, s78, 64
	s_addc_u32 s1, s79, 0
	v_writelane_b32 v254, s0, 47
	v_mbcnt_lo_u32_b32 v0, -1, 0
	s_nop 0
	v_writelane_b32 v254, s1, 48
	v_readlane_b32 s0, v252, 1
	v_readlane_b32 s1, v252, 2
	s_add_u32 s2, s0, 0x100
	s_addc_u32 s3, s1, 0
	v_writelane_b32 v254, s2, 49
	v_mbcnt_hi_u32_b32 v202, -1, v0
	s_nop 0
	v_writelane_b32 v254, s3, 50
	s_add_u32 s2, s0, 0x140
	s_addc_u32 s3, s1, 0
	v_writelane_b32 v254, s2, 51
	s_nop 1
	v_writelane_b32 v254, s3, 52
	s_add_u32 s2, s0, 0x180
	s_addc_u32 s3, s1, 0
	v_writelane_b32 v254, s2, 53
	s_add_u32 s0, s0, 0x1c0
	s_addc_u32 s1, s1, 0
	v_writelane_b32 v254, s3, 54
	v_writelane_b32 v254, s0, 55
	s_mov_b32 s2, s52
	s_nop 0
	v_writelane_b32 v254, s1, 56
	s_add_u32 s0, s78, 0x2c00
	s_addc_u32 s1, s79, 0
	v_writelane_b32 v254, s0, 57
	s_nop 1
	v_writelane_b32 v254, s1, 58
	v_writelane_b32 v254, s54, 59
	v_writelane_b32 v254, s52, 60
	s_nop 1
	v_writelane_b32 v254, s53, 61
	s_branch .LBB0_9

.LBB0_171:
	s_add_i32 s49, s49, 1
	s_lshl_b32 s26, s49, 3
	v_readlane_b32 s6, v254, 36
	s_or_b32 s26, s26, s6
	s_mul_i32 s34, s26, s46
	v_readlane_b32 s6, v254, 30
	s_add_i32 s34, s34, s6
	s_sub_u32 s26, s34, 0x1000
	s_cmp_lt_u32 s26, 0x200
	s_cbranch_scc0 .Ltailfix_0
	s_bfe_u32 s34, s101, 0x80010
	s_add_u32 s34, s34, 0x1000
	s_bitcmp1_b32 s101, 24
	s_cselect_b32 s34, s34, 0x7fff
.Ltailfix_0:
	s_cmpk_lt_i32 s34, 0x1100
	s_cselect_b64 s[30:31], -1, 0
	s_cmpk_gt_i32 s34, 0x10ff
	s_cselect_b64 s[26:27], -1, 0
	s_and_b64 vcc, exec, s[26:27]
	s_cbranch_vccnz .LBB0_173
	s_ashr_i32 s1, s34, 31
	s_lshr_b32 s1, s1, 24
	s_add_i32 s1, s34, s1
	s_ashr_i32 s3, s1, 8
	s_lshl_b32 s1, s3, 10
	s_lshl_b32 s35, s34, 7
	s_lshl_b32 s3, s3, 12
	s_lshl_b32 s34, s34, 4
	s_and_b32 s35, s35, 0x380
	s_sub_i32 s3, s34, s3
	s_or_b32 s1, s1, s35
	s_and_b32 s3, s3, 0xffffff80

.LBB0_277:
	s_andn2_b64 vcc, exec, s[0:1]
	s_cbranch_vccnz .LBB0_284
	v_readlane_b32 s20, v253, 13
	v_readlane_b32 s21, v253, 14
	v_readlane_b32 s34, v252, 0
	v_readlane_b32 s99, v254, 62
	s_load_dword s16, s[20:21], 0x0
	s_sub_u32 s20, s20, 0x218
	s_subb_u32 s21, s21, 0
	s_load_dwordx2 s[2:3], s[20:21], 0x138
	s_load_dwordx2 s[8:9], s[20:21], 0x150
	s_load_dwordx2 s[6:7], s[20:21], 0x158
	s_load_dwordx2 s[0:1], s[20:21], 0x160
	v_lshrrev_b32_e32 v0, 3, v194
	v_lshrrev_b32_e32 v1, 4, v194
	v_xor_b32_e32 v1, v1, v194
	v_and_b32_e32 v1, 7, v1
	v_lshlrev_b32_e32 v1, 4, v1
	v_add_u32_e32 v3, 0, v0
	v_lshl_or_b32 v132, v3, 12, v1
	v_lshl_or_b32 v222, v3, 10, v1
	v_add_u32_e32 v3, 32, v0
	v_lshl_or_b32 v133, v3, 12, v1
	v_lshl_or_b32 v223, v3, 10, v1
	v_add_u32_e32 v3, 64, v0
	v_lshl_or_b32 v134, v3, 12, v1
	v_lshl_or_b32 v224, v3, 10, v1
	v_add_u32_e32 v3, 96, v0
	v_lshl_or_b32 v135, v3, 12, v1
	v_lshl_or_b32 v225, v3, 10, v1
	v_and_b32_e32 v0, 15, v194
	v_lshrrev_b32_e32 v1, 1, v0
	v_bfe_u32 v3, v194, 4, 2
	v_xor_b32_e32 v1, v1, v3
	v_lshlrev_b32_e32 v1, 4, v1
	v_lshl_or_b32 v1, v0, 7, v1
	v_lshrrev_b32_e32 v3, 7, v194
	v_lshl_or_b32 v226, v3, 13, v1
	v_bfe_u32 v3, v194, 6, 1
	v_lshl_or_b32 v3, v3, 13, v1
	v_or_b32_e32 v228, 0x4000, v3
	v_xor_b32_e32 v227, 64, v226
	v_xor_b32_e32 v229, 64, v228
	v_lshrrev_b32_e32 v1, 7, v194
	v_lshl_or_b32 v0, v1, 6, v0
	v_bfe_u32 v1, v194, 6, 1
	v_lshlrev_b32_e32 v1, 6, v1
	v_bfe_u32 v3, v194, 4, 2
	v_lshl_or_b32 v1, v3, 2, v1
	v_lshlrev_b32_e32 v1, 1, v1
	v_add_u32_e32 v3, 0, v0
	v_lshl_or_b32 v230, v3, 13, v1
	v_lshl_or_b32 v234, v3, 11, v1
	v_add_u32_e32 v3, 16, v0
	v_lshl_or_b32 v231, v3, 13, v1
	v_lshl_or_b32 v235, v3, 11, v1
	v_add_u32_e32 v3, 32, v0
	v_lshl_or_b32 v232, v3, 13, v1
	v_lshl_or_b32 v236, v3, 11, v1
	v_add_u32_e32 v3, 48, v0
	v_lshl_or_b32 v233, v3, 13, v1
	v_lshl_or_b32 v237, v3, 11, v1
	v_lshrrev_b32_e32 v0, 6, v194
	v_lshlrev_b32_e32 v0, 10, v0
	s_nop 0
	v_readfirstlane_b32 s100, v0
	v_mov_b64_e32 v[4:5], 0
	v_mov_b64_e32 v[6:7], 0
	v_mov_b64_e32 v[8:9], 0
	v_mov_b64_e32 v[10:11], 0
	v_mov_b64_e32 v[12:13], 0
	v_mov_b64_e32 v[14:15], 0
	v_mov_b64_e32 v[16:17], 0
	v_mov_b64_e32 v[18:19], 0
	v_mov_b64_e32 v[20:21], 0
	v_mov_b64_e32 v[22:23], 0
	v_mov_b64_e32 v[24:25], 0
	v_mov_b64_e32 v[26:27], 0
	v_mov_b64_e32 v[28:29], 0
	v_mov_b64_e32 v[30:31], 0
	v_mov_b64_e32 v[32:33], 0
	v_mov_b64_e32 v[34:35], 0
	v_mov_b64_e32 v[36:37], 0
	v_mov_b64_e32 v[38:39], 0
	v_mov_b64_e32 v[40:41], 0
	v_mov_b64_e32 v[42:43], 0
	v_mov_b64_e32 v[44:45], 0
	v_mov_b64_e32 v[46:47], 0
	v_mov_b64_e32 v[48:49], 0
	v_mov_b64_e32 v[50:51], 0
	v_mov_b64_e32 v[52:53], 0
	v_mov_b64_e32 v[54:55], 0
	v_mov_b64_e32 v[56:57], 0
	v_mov_b64_e32 v[58:59], 0
	v_mov_b64_e32 v[60:61], 0
	v_mov_b64_e32 v[62:63], 0
	v_mov_b64_e32 v[64:65], 0
	v_mov_b64_e32 v[66:67], 0
	v_mov_b64_e32 v[68:69], 0
	v_mov_b64_e32 v[70:71], 0
	v_mov_b64_e32 v[72:73], 0
	v_mov_b64_e32 v[74:75], 0
	v_mov_b64_e32 v[76:77], 0
	v_mov_b64_e32 v[78:79], 0
	v_mov_b64_e32 v[80:81], 0
	v_mov_b64_e32 v[82:83], 0
	v_mov_b64_e32 v[84:85], 0
	v_mov_b64_e32 v[86:87], 0
	v_mov_b64_e32 v[88:89], 0
	v_mov_b64_e32 v[90:91], 0
	v_mov_b64_e32 v[92:93], 0
	v_mov_b64_e32 v[94:95], 0
	v_mov_b64_e32 v[96:97], 0
	v_mov_b64_e32 v[98:99], 0
	v_mov_b64_e32 v[100:101], 0
	v_mov_b64_e32 v[102:103], 0
	v_mov_b64_e32 v[104:105], 0
	v_mov_b64_e32 v[106:107], 0
	v_mov_b64_e32 v[108:109], 0
	v_mov_b64_e32 v[110:111], 0
	v_mov_b64_e32 v[112:113], 0
	v_mov_b64_e32 v[114:115], 0
	v_mov_b64_e32 v[116:117], 0
	v_mov_b64_e32 v[118:119], 0
	v_mov_b64_e32 v[120:121], 0
	v_mov_b64_e32 v[122:123], 0
	v_mov_b64_e32 v[124:125], 0
	v_mov_b64_e32 v[126:127], 0
	v_mov_b64_e32 v[128:129], 0
	v_mov_b64_e32 v[130:131], 0
	s_waitcnt lgkmcnt(0)
	s_cmp_gt_i32 s99, 9
	s_cselect_b32 s99, 0x400000, 0
	s_add_u32 s2, s2, s99
	s_addc_u32 s3, s3, 0
	s_lshr_b32 s16, s16, 3
	s_mov_b32 s15, 0
	s_and_b32 s99, s34, 7
	s_lshl_b32 vcc_lo, s15, 3
	s_add_u32 s99, s99, vcc_lo
	s_mul_i32 s99, s99, s16
	s_lshr_b32 vcc_lo, s34, 3
	s_add_u32 s99, s99, vcc_lo
	s_sub_u32 vcc_lo, s99, 0x400
	s_cmp_lt_u32 vcc_lo, 0x200
	s_cbranch_scc0 .Lmg_tf_0
	s_bfe_u32 s99, s101, 0x80010
	s_add_u32 s99, s99, 0x400
	s_bitcmp1_b32 s101, 24
	s_cselect_b32 s99, s99, 0x7fff
.Lmg_tf_0:
	s_cmp_lt_u32 s99, 0x440
	s_cselect_b32 s17, 1, 0
	s_lshr_b32 vcc_lo, s99, 6
	s_lshl_b32 vcc_lo, vcc_lo, 3
	s_and_b32 vcc_hi, s99, 7
	s_add_u32 vcc_lo, vcc_lo, vcc_hi
	s_lshl_b32 s10, vcc_lo, 7
	s_bfe_u32 vcc_lo, s99, 0x30003
	s_lshl_b32 s11, vcc_lo, 7
	s_cmp_eq_u32 s17, 0
	s_cbranch_scc1 .Lmg_exit
	s_mov_b32 s15, 1
	s_and_b32 s99, s34, 7
	s_lshl_b32 vcc_lo, s15, 3
	s_add_u32 s99, s99, vcc_lo
	s_mul_i32 s99, s99, s16
	s_lshr_b32 vcc_lo, s34, 3
	s_add_u32 s99, s99, vcc_lo
	s_sub_u32 vcc_lo, s99, 0x400
	s_cmp_lt_u32 vcc_lo, 0x200
	s_cbranch_scc0 .Lmg_tf_1
	s_bfe_u32 s99, s101, 0x80010
	s_add_u32 s99, s99, 0x400
	s_bitcmp1_b32 s101, 24
	s_cselect_b32 s99, s99, 0x7fff
.Lmg_tf_1:
	s_cmp_lt_u32 s99, 0x440
	s_cselect_b32 s17, 1, 0
	s_lshr_b32 vcc_lo, s99, 6
	s_lshl_b32 vcc_lo, vcc_lo, 3
	s_and_b32 vcc_hi, s99, 7
	s_add_u32 vcc_lo, vcc_lo, vcc_hi
	s_lshl_b32 s12, vcc_lo, 7
	s_bfe_u32 vcc_lo, s99, 0x30003
	s_lshl_b32 s13, vcc_lo, 7
	s_mov_b32 s14, 0
	s_bfe_u32 m0, s34, 0x20003
	s_add_u32 m0, m0, s14
	s_and_b32 m0, m0, 3
	s_lshl_b32 vcc_lo, s10, 12
	s_lshl_b32 vcc_hi, m0, 10
	s_add_u32 vcc_lo, vcc_lo, vcc_hi
	s_add_u32 s18, s0, vcc_lo
	s_addc_u32 s19, s1, 0
	s_lshl_b32 vcc_lo, s11, 10
	s_lshl_b32 vcc_hi, m0, 20
	s_add_u32 vcc_lo, vcc_lo, vcc_hi
	s_add_u32 s20, s2, vcc_lo
	s_addc_u32 s21, s3, 0
	s_bfe_u32 m0, s34, 0x20003
	s_add_u32 m0, m0, s14
	s_and_b32 m0, m0, 3
	s_lshl_b32 vcc_lo, s10, 13
	s_lshl_b32 vcc_hi, m0, 11
	s_add_u32 vcc_lo, vcc_lo, vcc_hi
	s_lshl_b32 vcc_hi, s11, 1
	s_add_u32 vcc_lo, vcc_lo, vcc_hi
	s_add_u32 s38, s6, vcc_lo
	s_addc_u32 s39, s7, 0
	s_lshl_b32 vcc_lo, s10, 11
	s_lshl_b32 vcc_hi, s11, 1
	s_add_u32 vcc_lo, vcc_lo, vcc_hi
	s_add_u32 s40, s8, vcc_lo
	s_addc_u32 s41, s9, 0
	s_cmp_lt_u32 s14, 3
	s_cbranch_scc0 .Lmg_nt_0
	s_add_u32 s99, s14, 1
	s_bfe_u32 m0, s34, 0x20003
	s_add_u32 m0, m0, s99
	s_and_b32 m0, m0, 3
	s_lshl_b32 vcc_lo, s10, 12
	s_lshl_b32 vcc_hi, m0, 10
	s_add_u32 vcc_lo, vcc_lo, vcc_hi
	s_add_u32 s22, s0, vcc_lo
	s_addc_u32 s23, s1, 0
	s_lshl_b32 vcc_lo, s11, 10
	s_lshl_b32 vcc_hi, m0, 20
	s_add_u32 vcc_lo, vcc_lo, vcc_hi
	s_add_u32 s24, s2, vcc_lo
	s_addc_u32 s25, s3, 0
	s_mov_b32 s35, 1
	s_branch .Lmg_nd_0

.Lmg_nostore:
	v_mov_b64_e32 v[68:69], 0
	v_mov_b64_e32 v[70:71], 0
	v_mov_b64_e32 v[72:73], 0
	v_mov_b64_e32 v[74:75], 0
	v_mov_b64_e32 v[76:77], 0
	v_mov_b64_e32 v[78:79], 0
	v_mov_b64_e32 v[80:81], 0
	v_mov_b64_e32 v[82:83], 0
	v_mov_b64_e32 v[84:85], 0
	v_mov_b64_e32 v[86:87], 0
	v_mov_b64_e32 v[88:89], 0
	v_mov_b64_e32 v[90:91], 0
	v_mov_b64_e32 v[92:93], 0
	v_mov_b64_e32 v[94:95], 0
	v_mov_b64_e32 v[96:97], 0
	v_mov_b64_e32 v[98:99], 0
	v_mov_b64_e32 v[100:101], 0
	v_mov_b64_e32 v[102:103], 0
	v_mov_b64_e32 v[104:105], 0
	v_mov_b64_e32 v[106:107], 0
	v_mov_b64_e32 v[108:109], 0
	v_mov_b64_e32 v[110:111], 0
	v_mov_b64_e32 v[112:113], 0
	v_mov_b64_e32 v[114:115], 0
	v_mov_b64_e32 v[116:117], 0
	v_mov_b64_e32 v[118:119], 0
	v_mov_b64_e32 v[120:121], 0
	v_mov_b64_e32 v[122:123], 0
	v_mov_b64_e32 v[124:125], 0
	v_mov_b64_e32 v[126:127], 0
	v_mov_b64_e32 v[128:129], 0
	v_mov_b64_e32 v[130:131], 0
	s_cmp_eq_u32 s35, 0
	s_cbranch_scc1 .Lmg_exit
	s_mov_b64 s[18:19], s[22:23]
	s_mov_b64 s[20:21], s[24:25]
	s_cmp_lt_u32 s14, 3
	s_cbranch_scc1 .Lmg_sameb
	s_mov_b32 s14, 0
	s_mov_b32 s10, s12
	s_mov_b32 s11, s13
	s_add_u32 s15, s15, 1
	s_and_b32 s99, s34, 7
	s_lshl_b32 vcc_lo, s15, 3
	s_add_u32 s99, s99, vcc_lo
	s_mul_i32 s99, s99, s16
	s_lshr_b32 vcc_lo, s34, 3
	s_add_u32 s99, s99, vcc_lo
	s_sub_u32 vcc_lo, s99, 0x400
	s_cmp_lt_u32 vcc_lo, 0x200
	s_cbranch_scc0 .Lmg_tf_2
	s_bfe_u32 s99, s101, 0x80010
	s_add_u32 s99, s99, 0x400
	s_bitcmp1_b32 s101, 24
	s_cselect_b32 s99, s99, 0x7fff
.Lmg_tf_2:
	s_cmp_lt_u32 s99, 0x440
	s_cselect_b32 s17, 1, 0
	s_lshr_b32 vcc_lo, s99, 6
	s_lshl_b32 vcc_lo, vcc_lo, 3
	s_and_b32 vcc_hi, s99, 7
	s_add_u32 vcc_lo, vcc_lo, vcc_hi
	s_lshl_b32 s12, vcc_lo, 7
	s_bfe_u32 vcc_lo, s99, 0x30003
	s_lshl_b32 s13, vcc_lo, 7
	s_branch .Lmg_advd

.LBB0_299:
	s_add_i32 s3, s3, 1
	s_lshl_b32 s26, s3, 3
	v_readlane_b32 s6, v254, 36
	s_or_b32 s26, s26, s6
	s_mul_i32 s34, s26, s46
	v_readlane_b32 s6, v254, 30
	s_add_i32 s34, s34, s6
	s_sub_u32 s26, s34, 0x1000
	s_cmp_lt_u32 s26, 0x200
	s_cbranch_scc0 .Ltailfix_1
	s_bfe_u32 s34, s101, 0x80010
	s_add_u32 s34, s34, 0x1000
	s_bitcmp1_b32 s101, 24
	s_cselect_b32 s34, s34, 0x7fff
.Ltailfix_1:
	s_cmpk_lt_i32 s34, 0x1100
	s_cselect_b64 s[30:31], -1, 0
	s_cmpk_gt_i32 s34, 0x10ff
	s_cselect_b64 s[26:27], -1, 0
	s_and_b64 vcc, exec, s[26:27]
	s_cbranch_vccnz .LBB0_301
	s_ashr_i32 s1, s34, 31
	s_lshr_b32 s1, s1, 24
	s_add_i32 s1, s34, s1
	s_ashr_i32 s1, s1, 8
	s_lshl_b32 s35, s1, 10
	s_lshl_b32 s38, s34, 7
	s_lshl_b32 s1, s1, 12
	s_lshl_b32 s34, s34, 4
	s_and_b32 s38, s38, 0x380
	s_sub_i32 s1, s34, s1
	s_or_b32 s49, s35, s38
	s_and_b32 s1, s1, 0xffffff80

.LBB0_323:
	s_add_i32 s3, s3, 1
	s_lshl_b32 s26, s3, 3
	v_readlane_b32 s5, v254, 36
	s_or_b32 s26, s26, s5
	s_mul_i32 s34, s26, s46
	v_readlane_b32 s5, v254, 30
	s_add_i32 s34, s34, s5
	s_sub_u32 s26, s34, 0x200
	s_cmp_lt_u32 s26, 0x200
	s_cbranch_scc0 .Ltailfix_2
	s_bfe_u32 s34, s101, 0x80010
	s_add_u32 s34, s34, 0x200
	s_bitcmp1_b32 s101, 24
	s_cselect_b32 s34, s34, 0x7fff
.Ltailfix_2:
	s_cmpk_lt_i32 s34, 0x220
	s_cselect_b64 s[30:31], -1, 0
	s_cmpk_gt_i32 s34, 0x21f
	s_cselect_b64 s[26:27], -1, 0
	s_and_b64 vcc, exec, s[26:27]
	s_cbranch_vccnz .LBB0_325
	s_ashr_i32 s1, s34, 31
	s_lshr_b32 s1, s1, 27
	s_add_i32 s1, s34, s1
	s_ashr_i32 s1, s1, 5
	s_lshl_b32 s35, s1, 10
	s_lshl_b32 s38, s34, 7
	s_lshl_b32 s1, s1, 9
	s_lshl_b32 s34, s34, 4
	s_and_b32 s38, s38, 0x380
	s_sub_i32 s1, s34, s1
	s_or_b32 s49, s35, s38
	s_and_b32 s1, s1, 0xffffff80

.LBB0_946:
	s_add_i32 s3, s3, 1
	s_lshl_b32 s26, s3, 3
	v_readlane_b32 s4, v254, 36
	s_or_b32 s26, s26, s4
	s_mul_i32 s34, s26, s46
	v_readlane_b32 s4, v254, 30
	s_add_i32 s34, s34, s4
	s_sub_u32 s26, s34, 0x1a00
	s_cmp_lt_u32 s26, 0x200
	s_cbranch_scc0 .Ltailfix_3
	s_bfe_u32 s34, s101, 0x80010
	s_add_u32 s34, s34, 0x1a00
	s_bitcmp1_b32 s101, 24
	s_cselect_b32 s34, s34, 0x7fff
.Ltailfix_3:
	s_cmpk_lt_i32 s34, 0x1a08
	s_cselect_b64 s[30:31], -1, 0
	s_cmpk_gt_i32 s34, 0x1a07
	s_cselect_b64 s[26:27], -1, 0
	s_and_b64 vcc, exec, s[26:27]
	s_cbranch_vccnz .LBB0_948
	s_mul_hi_i32 s1, s34, 0x5397829d
	s_lshr_b32 s35, s1, 31
	s_ashr_i32 s1, s1, 7
	s_add_i32 s1, s1, s35
	s_mul_i32 s35, s1, 0xfffffe78
	s_add_i32 s35, s35, s34
	s_lshl_b32 s34, s34, 7
	s_lshl_b32 s1, s1, 10
	s_and_b32 s34, s34, 0x380
	s_or_b32 s48, s1, s34
	s_lshl_b32 s1, s35, 4
	s_and_b32 s1, s1, 0xffffff80
